# SwiGLU K-loop: vmcnt(16) instead of vmcnt(8) in the first iteration of non-first units so the load-segment waits do not depend on the epilogue stores
# baseline (speedup 1.0000x reference)
; #define PG8_STAGE(bufoff, gbase, voff) do { _Pragma("unroll") for (int _i = 0; _i < 2; ++_i) \
;         __builtin_amdgcn_global_load_lds((const unsigned*)((const char*)(gbase) + (voff)[_i]), (LAS unsigned*)(lds + (bufoff) + ldsw + _i * 8192), 16, 0, 0); } while (0)
; #define PG8_LDA(dst, b, h) do { _Pragma("unroll") for (int m = 0; m < 4; ++m) _Pragma("unroll") for (int k = 0; k < 2; ++k) dst[m][k] = *(const LAS bf16x8*)(lds + PG8_SA(b, h) + aoff + m * 2048 + k * 1024); } while (0)
; #define PG8_LDB(dst, b, h) do { _Pragma("unroll") for (int n = 0; n < 2; ++n) _Pragma("unroll") for (int k = 0; k < 2; ++k) dst[n][k] = *(const LAS bf16x8*)(lds + PG8_SB(b, h) + boff + n * 2048 + k * 1024); } while (0)
; #define PG8_MMA(ai, bj, At, Bt) do { __builtin_amdgcn_s_setprio(1); _Pragma("unroll") for (int m = 0; m < 4; ++m) _Pragma("unroll") for (int n = 0; n < 2; ++n) _Pragma("unroll") for (int k = 0; k < 2; ++k) \
;         acc[ai][bj][m][n] = __builtin_amdgcn_mfma_f32_16x16x32_bf16(Bt[n][k], At[m][k], acc[ai][bj][m][n], 0, 0, 0); __builtin_amdgcn_s_setprio(0); } while (0)
; #define PG8_WAIT_V(n) asm volatile("s_waitcnt vmcnt(" #n ")" ::: "memory")
; #define PG8_WAIT_L(n) asm volatile("s_waitcnt lgkmcnt(" #n ")" ::: "memory")
; #define PG8_BAR __builtin_amdgcn_s_barrier()
; #define PG8_SCHED __builtin_amdgcn_sched_barrier(0)
; template <class Epi, class Sched>
; __device__ __forceinline__ void gemm_phase(LAS unsigned char* lds, const Gemm g, const Sched& S, const Epi& E) {
;     ...
;             const bool last = (t == nt - 2);
;             const char* a1 = cA + (size_t)(t + 1) * kstep;
;             const char* a2 = last ? nA : cA + (size_t)(t + 2) * kstep; const char* b2 = last ? nB : cB + (size_t)(t + 2) * kstep;
;             const char* a3 = a2 + kstep; const char* b3 = b2 + kstep;
;             PG8_LDB(B0, 0, 0); PG8_LDB(B1, 0, 1); PG8_SCHED; PG8_LDA(At, 0, 0); PG8_STAGE(PG8_SA(1, 1), a1 + hstep, voffA);
;             PG8_WAIT_V(8); PG8_WAIT_L(0); PG8_BAR; PG8_MMA(0, 0, At, B0); PG8_MMA(0, 1, At, B1); PG8_BAR; PG8_SCHED;
.LBB0_744:
	s_add_u32 s24, s22, 0xfffc0080
	s_addc_u32 s25, s23, -1
	s_add_i32 s49, 0, 0x10000
	s_cmp_eq_u32 s48, 12
	s_cselect_b32 s27, s15, s25
	s_cselect_b32 s26, s44, s24
	s_cselect_b32 s25, s17, s47
	s_cselect_b32 s24, s45, s46
	s_add_i32 s52, 0, 0x14000
	v_add_u32_e32 v140, s49, v162
	v_add_u32_e32 v158, s52, v162
	ds_read_b128 v[128:131], v140
	ds_read_b128 v[132:135], v140 offset:1024
	ds_read_b128 v[136:139], v140 offset:2048
	ds_read_b128 v[140:143], v140 offset:3072
	ds_read_b128 v[154:157], v158
	ds_read_b128 v[164:167], v158 offset:1024
	ds_read_b128 v[168:171], v158 offset:2048
	ds_read_b128 v[172:175], v158 offset:3072
	v_lshl_add_u64 v[158:159], s[22:23], 0, v[150:151]
	s_add_i32 m0, s28, 0xc000
	ds_read_b128 v[176:179], v163
	ds_read_b128 v[192:195], v163 offset:1024
	ds_read_b128 v[196:199], v163 offset:2048
	ds_read_b128 v[200:203], v163 offset:3072
	ds_read_b128 v[204:207], v163 offset:4096
	ds_read_b128 v[208:211], v163 offset:5120
	ds_read_b128 v[212:215], v163 offset:6144
	ds_read_b128 v[230:233], v163 offset:7168
	global_load_lds_dwordx4 v[158:159], off
	v_lshl_add_u64 v[158:159], s[22:23], 0, v[152:153]
	s_add_i32 m0, s28, 0xe000
	s_nop 0
	global_load_lds_dwordx4 v[158:159], off
	s_cmp_lg_u32 s48, 0xfffffffe
	s_cbranch_scc1 .Lfw3_n1
	s_cmp_lt_u32 s42, 2
	s_cbranch_scc1 .Lfw3_n1
	s_waitcnt vmcnt(16)
	s_branch .Lfw3_d1

; #define PG8_STAGE(bufoff, gbase, voff) do { _Pragma("unroll") for (int _i = 0; _i < 2; ++_i) \
;         __builtin_amdgcn_global_load_lds((const unsigned*)((const char*)(gbase) + (voff)[_i]), (LAS unsigned*)(lds + (bufoff) + ldsw + _i * 8192), 16, 0, 0); } while (0)
; #define PG8_LDA(dst, b, h) do { _Pragma("unroll") for (int m = 0; m < 4; ++m) _Pragma("unroll") for (int k = 0; k < 2; ++k) dst[m][k] = *(const LAS bf16x8*)(lds + PG8_SA(b, h) + aoff + m * 2048 + k * 1024); } while (0)
; #define PG8_MMA(ai, bj, At, Bt) do { __builtin_amdgcn_s_setprio(1); _Pragma("unroll") for (int m = 0; m < 4; ++m) _Pragma("unroll") for (int n = 0; n < 2; ++n) _Pragma("unroll") for (int k = 0; k < 2; ++k) \
;         acc[ai][bj][m][n] = __builtin_amdgcn_mfma_f32_16x16x32_bf16(Bt[n][k], At[m][k], acc[ai][bj][m][n], 0, 0, 0); __builtin_amdgcn_s_setprio(0); } while (0)
; #define PG8_WAIT_V(n) asm volatile("s_waitcnt vmcnt(" #n ")" ::: "memory")
; #define PG8_WAIT_L(n) asm volatile("s_waitcnt lgkmcnt(" #n ")" ::: "memory")
; #define PG8_BAR __builtin_amdgcn_s_barrier()
; #define PG8_SCHED __builtin_amdgcn_sched_barrier(0)
; template <class Epi, class Sched>
; __device__ __forceinline__ void gemm_phase(LAS unsigned char* lds, const Gemm g, const Sched& S, const Epi& E) {
;     ...
;             PG8_WAIT_V(8); PG8_WAIT_L(0); PG8_BAR; PG8_MMA(0, 0, At, B0); PG8_MMA(0, 1, At, B1); PG8_BAR; PG8_SCHED;
;             PG8_LDA(At, 0, 1); PG8_STAGE(PG8_SB(0, 0), b2, voffB); PG8_STAGE(PG8_SB(0, 1), b2 + hstep, voffB); PG8_STAGE(PG8_SA(0, 0), a2, voffA);
;             PG8_WAIT_V(8); PG8_WAIT_L(0); PG8_BAR; PG8_MMA(1, 0, At, B0); PG8_MMA(1, 1, At, B1); PG8_BAR; PG8_SCHED;
.Lfw3_d1:
	s_waitcnt lgkmcnt(0)
	s_barrier
	s_setprio 1
	s_waitcnt lgkmcnt(0)
	v_mfma_f32_16x16x32_bf16 v[124:127], v[128:131], v[176:179], v[124:127]
	v_mfma_f32_16x16x32_bf16 v[120:123], v[136:139], v[176:179], v[120:123]
	v_mfma_f32_16x16x32_bf16 v[108:111], v[128:131], v[196:199], v[108:111]
	v_mfma_f32_16x16x32_bf16 v[104:107], v[136:139], v[196:199], v[104:107]
	v_mfma_f32_16x16x32_bf16 v[92:95], v[128:131], v[204:207], v[92:95]
	v_mfma_f32_16x16x32_bf16 v[88:91], v[136:139], v[204:207], v[88:91]
	v_mfma_f32_16x16x32_bf16 v[76:79], v[128:131], v[212:215], v[76:79]
	v_mfma_f32_16x16x32_bf16 v[72:75], v[136:139], v[212:215], v[72:75]
	v_mfma_f32_16x16x32_bf16 v[124:127], v[132:135], v[192:195], v[124:127]
	v_mfma_f32_16x16x32_bf16 v[120:123], v[140:143], v[192:195], v[120:123]
	v_mfma_f32_16x16x32_bf16 v[108:111], v[132:135], v[200:203], v[108:111]
	v_mfma_f32_16x16x32_bf16 v[104:107], v[140:143], v[200:203], v[104:107]
	v_mfma_f32_16x16x32_bf16 v[92:95], v[132:135], v[208:211], v[92:95]
	v_mfma_f32_16x16x32_bf16 v[88:91], v[140:143], v[208:211], v[88:91]
	v_mfma_f32_16x16x32_bf16 v[76:79], v[132:135], v[230:233], v[76:79]
	v_mfma_f32_16x16x32_bf16 v[72:75], v[140:143], v[230:233], v[72:75]
	s_setprio 0
	s_setprio 1
	v_mfma_f32_16x16x32_bf16 v[112:115], v[154:157], v[176:179], v[112:115]
	v_mfma_f32_16x16x32_bf16 v[116:119], v[168:171], v[176:179], v[116:119]
	v_mfma_f32_16x16x32_bf16 v[96:99], v[154:157], v[196:199], v[96:99]
	v_mfma_f32_16x16x32_bf16 v[100:103], v[168:171], v[196:199], v[100:103]
	v_mfma_f32_16x16x32_bf16 v[80:83], v[154:157], v[204:207], v[80:83]
	v_mfma_f32_16x16x32_bf16 v[84:87], v[168:171], v[204:207], v[84:87]
	v_mfma_f32_16x16x32_bf16 v[64:67], v[154:157], v[212:215], v[64:67]
	v_mfma_f32_16x16x32_bf16 v[68:71], v[168:171], v[212:215], v[68:71]
	v_mfma_f32_16x16x32_bf16 v[112:115], v[164:167], v[192:195], v[112:115]
	v_mfma_f32_16x16x32_bf16 v[116:119], v[172:175], v[192:195], v[116:119]
	v_mfma_f32_16x16x32_bf16 v[96:99], v[164:167], v[200:203], v[96:99]
	v_mfma_f32_16x16x32_bf16 v[100:103], v[172:175], v[200:203], v[100:103]
	v_mfma_f32_16x16x32_bf16 v[80:83], v[164:167], v[208:211], v[80:83]
	v_mfma_f32_16x16x32_bf16 v[84:87], v[172:175], v[208:211], v[84:87]
	v_mfma_f32_16x16x32_bf16 v[64:67], v[164:167], v[230:233], v[64:67]
	v_mfma_f32_16x16x32_bf16 v[68:71], v[172:175], v[230:233], v[68:71]
	s_setprio 0
	s_barrier
	s_add_i32 s49, s49, s8
	v_lshl_add_u64 v[158:159], s[24:25], 0, v[184:185]
	s_mov_b32 m0, s49
	ds_read_b128 v[176:179], v163 offset:16384
	ds_read_b128 v[192:195], v163 offset:17408
	ds_read_b128 v[196:199], v163 offset:18432
	ds_read_b128 v[200:203], v163 offset:19456
	ds_read_b128 v[204:207], v163 offset:20480
	ds_read_b128 v[208:211], v163 offset:21504
	ds_read_b128 v[212:215], v163 offset:22528
	ds_read_b128 v[230:233], v163 offset:23552
	global_load_lds_dwordx4 v[158:159], off
	s_add_i32 m0, s49, 0x2000
	s_add_u32 s50, s24, 0x40000
	v_lshl_add_u64 v[216:217], s[24:25], 0, v[144:145]
	s_addc_u32 s51, s25, 0
	s_add_i32 s49, s52, s8
	global_load_lds_dwordx4 v[216:217], off
	v_lshl_add_u64 v[234:235], s[50:51], 0, v[184:185]
	s_mov_b32 m0, s49
	v_lshl_add_u64 v[236:237], s[26:27], 0, v[146:147]
	global_load_lds_dwordx4 v[234:235], off
	v_lshl_add_u64 v[234:235], s[50:51], 0, v[144:145]
	s_add_i32 m0, s49, 0x2000
	s_nop 0
	global_load_lds_dwordx4 v[234:235], off
	v_lshl_add_u64 v[234:235], s[26:27], 0, v[148:149]
	s_mov_b32 m0, s28
	s_nop 0
	global_load_lds_dwordx4 v[234:235], off
	s_mov_b32 m0, s29
	s_nop 0
	global_load_lds_dwordx4 v[236:237], off
	s_cmp_lg_u32 s48, 0xfffffffe
	s_cbranch_scc1 .Lfw3_n2
	s_cmp_lt_u32 s42, 2
	s_cbranch_scc1 .Lfw3_n2
	s_waitcnt vmcnt(16)
	s_branch .Lfw3_d2

; #define PG8_STAGE(bufoff, gbase, voff) do { _Pragma("unroll") for (int _i = 0; _i < 2; ++_i) \
;         __builtin_amdgcn_global_load_lds((const unsigned*)((const char*)(gbase) + (voff)[_i]), (LAS unsigned*)(lds + (bufoff) + ldsw + _i * 8192), 16, 0, 0); } while (0)
; #define PG8_LDA(dst, b, h) do { _Pragma("unroll") for (int m = 0; m < 4; ++m) _Pragma("unroll") for (int k = 0; k < 2; ++k) dst[m][k] = *(const LAS bf16x8*)(lds + PG8_SA(b, h) + aoff + m * 2048 + k * 1024); } while (0)
; #define PG8_LDB(dst, b, h) do { _Pragma("unroll") for (int n = 0; n < 2; ++n) _Pragma("unroll") for (int k = 0; k < 2; ++k) dst[n][k] = *(const LAS bf16x8*)(lds + PG8_SB(b, h) + boff + n * 2048 + k * 1024); } while (0)
; #define PG8_MMA(ai, bj, At, Bt) do { __builtin_amdgcn_s_setprio(1); _Pragma("unroll") for (int m = 0; m < 4; ++m) _Pragma("unroll") for (int n = 0; n < 2; ++n) _Pragma("unroll") for (int k = 0; k < 2; ++k) \
;         acc[ai][bj][m][n] = __builtin_amdgcn_mfma_f32_16x16x32_bf16(Bt[n][k], At[m][k], acc[ai][bj][m][n], 0, 0, 0); __builtin_amdgcn_s_setprio(0); } while (0)
; #define PG8_WAIT_V(n) asm volatile("s_waitcnt vmcnt(" #n ")" ::: "memory")
; #define PG8_WAIT_L(n) asm volatile("s_waitcnt lgkmcnt(" #n ")" ::: "memory")
; #define PG8_BAR __builtin_amdgcn_s_barrier()
; #define PG8_SCHED __builtin_amdgcn_sched_barrier(0)
; template <class Epi, class Sched>
; __device__ __forceinline__ void gemm_phase(LAS unsigned char* lds, const Gemm g, const Sched& S, const Epi& E) {
;     ...
;             PG8_WAIT_V(8); PG8_WAIT_L(0); PG8_BAR; PG8_MMA(1, 0, At, B0); PG8_MMA(1, 1, At, B1); PG8_BAR; PG8_SCHED;
;             PG8_LDB(B0, 1, 0); PG8_LDB(B1, 1, 1); PG8_SCHED; PG8_LDA(At, 1, 0); PG8_STAGE(PG8_SA(0, 1), a2 + hstep, voffA);
;             PG8_WAIT_V(8); PG8_WAIT_L(0); PG8_BAR; PG8_MMA(0, 0, At, B0); PG8_MMA(0, 1, At, B1); PG8_BAR; PG8_SCHED;
.Lfw3_d2:
	s_waitcnt lgkmcnt(0)
	s_barrier
	s_setprio 1
	s_waitcnt lgkmcnt(0)
	v_mfma_f32_16x16x32_bf16 v[60:63], v[128:131], v[176:179], v[60:63]
	v_mfma_f32_16x16x32_bf16 v[56:59], v[136:139], v[176:179], v[56:59]
	v_mfma_f32_16x16x32_bf16 v[44:47], v[128:131], v[196:199], v[44:47]
	v_mfma_f32_16x16x32_bf16 v[40:43], v[136:139], v[196:199], v[40:43]
	v_mfma_f32_16x16x32_bf16 v[28:31], v[128:131], v[204:207], v[28:31]
	v_mfma_f32_16x16x32_bf16 v[24:27], v[136:139], v[204:207], v[24:27]
	v_mfma_f32_16x16x32_bf16 v[12:15], v[128:131], v[212:215], v[12:15]
	v_mfma_f32_16x16x32_bf16 v[8:11], v[136:139], v[212:215], v[8:11]
	v_mfma_f32_16x16x32_bf16 v[60:63], v[132:135], v[192:195], v[60:63]
	v_mfma_f32_16x16x32_bf16 v[56:59], v[140:143], v[192:195], v[56:59]
	v_mfma_f32_16x16x32_bf16 v[44:47], v[132:135], v[200:203], v[44:47]
	v_mfma_f32_16x16x32_bf16 v[40:43], v[140:143], v[200:203], v[40:43]
	v_mfma_f32_16x16x32_bf16 v[28:31], v[132:135], v[208:211], v[28:31]
	v_mfma_f32_16x16x32_bf16 v[24:27], v[140:143], v[208:211], v[24:27]
	v_mfma_f32_16x16x32_bf16 v[12:15], v[132:135], v[230:233], v[12:15]
	v_mfma_f32_16x16x32_bf16 v[8:11], v[140:143], v[230:233], v[8:11]
	s_setprio 0
	s_setprio 1
	v_mfma_f32_16x16x32_bf16 v[48:51], v[154:157], v[176:179], v[48:51]
	v_mfma_f32_16x16x32_bf16 v[52:55], v[168:171], v[176:179], v[52:55]
	v_mfma_f32_16x16x32_bf16 v[32:35], v[154:157], v[196:199], v[32:35]
	v_mfma_f32_16x16x32_bf16 v[36:39], v[168:171], v[196:199], v[36:39]
	v_mfma_f32_16x16x32_bf16 v[16:19], v[154:157], v[204:207], v[16:19]
	v_mfma_f32_16x16x32_bf16 v[20:23], v[168:171], v[204:207], v[20:23]
	v_mfma_f32_16x16x32_bf16 v[0:3], v[154:157], v[212:215], v[0:3]
	v_mfma_f32_16x16x32_bf16 v[4:7], v[168:171], v[212:215], v[4:7]
	v_mfma_f32_16x16x32_bf16 v[48:51], v[164:167], v[192:195], v[48:51]
	v_mfma_f32_16x16x32_bf16 v[52:55], v[172:175], v[192:195], v[52:55]
	v_mfma_f32_16x16x32_bf16 v[32:35], v[164:167], v[200:203], v[32:35]
	v_mfma_f32_16x16x32_bf16 v[36:39], v[172:175], v[200:203], v[36:39]
	v_mfma_f32_16x16x32_bf16 v[16:19], v[164:167], v[208:211], v[16:19]
	v_mfma_f32_16x16x32_bf16 v[20:23], v[172:175], v[208:211], v[20:23]
	v_mfma_f32_16x16x32_bf16 v[0:3], v[164:167], v[230:233], v[0:3]
	v_mfma_f32_16x16x32_bf16 v[4:7], v[172:175], v[230:233], v[4:7]
	s_setprio 0
	s_barrier
	s_add_i32 s49, 0, 0x18000
	s_add_i32 s50, 0, 0x1c000
	v_add_u32_e32 v140, s49, v162
	v_add_u32_e32 v172, s50, v162
	ds_read_b128 v[128:131], v140
	ds_read_b128 v[132:135], v140 offset:1024
	ds_read_b128 v[136:139], v140 offset:2048
	ds_read_b128 v[140:143], v140 offset:3072
	ds_read_b128 v[154:157], v172
	ds_read_b128 v[164:167], v172 offset:1024
	ds_read_b128 v[168:171], v172 offset:2048
	ds_read_b128 v[172:175], v172 offset:3072
	s_add_u32 s26, s26, 0x40000
	s_addc_u32 s27, s27, 0
	s_mov_b32 m0, s30
	v_lshl_add_u64 v[238:239], s[26:27], 0, v[148:149]
	ds_read_b128 v[176:179], v163 offset:32768
	ds_read_b128 v[192:195], v163 offset:33792
	ds_read_b128 v[196:199], v163 offset:34816
	ds_read_b128 v[200:203], v163 offset:35840
	ds_read_b128 v[204:207], v163 offset:36864
	ds_read_b128 v[208:211], v163 offset:37888
	ds_read_b128 v[212:215], v163 offset:38912
	ds_read_b128 v[230:233], v163 offset:39936
	global_load_lds_dwordx4 v[238:239], off
	v_lshl_add_u64 v[238:239], s[26:27], 0, v[146:147]
	s_mov_b32 m0, s31
	s_nop 0
	global_load_lds_dwordx4 v[238:239], off
	s_waitcnt vmcnt(8)
	s_waitcnt lgkmcnt(0)
	s_barrier
	s_setprio 1
	s_waitcnt lgkmcnt(0)
	v_mfma_f32_16x16x32_bf16 v[124:127], v[128:131], v[176:179], v[124:127]
	v_mfma_f32_16x16x32_bf16 v[120:123], v[136:139], v[176:179], v[120:123]
	v_mfma_f32_16x16x32_bf16 v[108:111], v[128:131], v[196:199], v[108:111]
	v_mfma_f32_16x16x32_bf16 v[104:107], v[136:139], v[196:199], v[104:107]
	v_mfma_f32_16x16x32_bf16 v[92:95], v[128:131], v[204:207], v[92:95]
	v_mfma_f32_16x16x32_bf16 v[88:91], v[136:139], v[204:207], v[88:91]
	v_mfma_f32_16x16x32_bf16 v[76:79], v[128:131], v[212:215], v[76:79]
	v_mfma_f32_16x16x32_bf16 v[72:75], v[136:139], v[212:215], v[72:75]
	v_mfma_f32_16x16x32_bf16 v[124:127], v[132:135], v[192:195], v[124:127]
	v_mfma_f32_16x16x32_bf16 v[120:123], v[140:143], v[192:195], v[120:123]
	v_mfma_f32_16x16x32_bf16 v[108:111], v[132:135], v[200:203], v[108:111]
	v_mfma_f32_16x16x32_bf16 v[104:107], v[140:143], v[200:203], v[104:107]
	v_mfma_f32_16x16x32_bf16 v[92:95], v[132:135], v[208:211], v[92:95]
	v_mfma_f32_16x16x32_bf16 v[88:91], v[140:143], v[208:211], v[88:91]
	v_mfma_f32_16x16x32_bf16 v[76:79], v[132:135], v[230:233], v[76:79]
	v_mfma_f32_16x16x32_bf16 v[72:75], v[140:143], v[230:233], v[72:75]
	s_setprio 0
	s_setprio 1
	v_mfma_f32_16x16x32_bf16 v[112:115], v[154:157], v[176:179], v[112:115]
	v_mfma_f32_16x16x32_bf16 v[116:119], v[168:171], v[176:179], v[116:119]
	v_mfma_f32_16x16x32_bf16 v[96:99], v[154:157], v[196:199], v[96:99]
	v_mfma_f32_16x16x32_bf16 v[100:103], v[168:171], v[196:199], v[100:103]
	v_mfma_f32_16x16x32_bf16 v[80:83], v[154:157], v[204:207], v[80:83]
	v_mfma_f32_16x16x32_bf16 v[84:87], v[168:171], v[204:207], v[84:87]
	v_mfma_f32_16x16x32_bf16 v[64:67], v[154:157], v[212:215], v[64:67]
	v_mfma_f32_16x16x32_bf16 v[68:71], v[168:171], v[212:215], v[68:71]
	v_mfma_f32_16x16x32_bf16 v[112:115], v[164:167], v[192:195], v[112:115]
	v_mfma_f32_16x16x32_bf16 v[116:119], v[172:175], v[192:195], v[116:119]
	v_mfma_f32_16x16x32_bf16 v[96:99], v[164:167], v[200:203], v[96:99]
	v_mfma_f32_16x16x32_bf16 v[100:103], v[172:175], v[200:203], v[100:103]
	v_mfma_f32_16x16x32_bf16 v[80:83], v[164:167], v[208:211], v[80:83]
	v_mfma_f32_16x16x32_bf16 v[84:87], v[172:175], v[208:211], v[84:87]
	v_mfma_f32_16x16x32_bf16 v[64:67], v[164:167], v[230:233], v[64:67]
	v_mfma_f32_16x16x32_bf16 v[68:71], v[172:175], v[230:233], v[68:71]
	s_setprio 0
	s_barrier
; #define PG8_STAGE(bufoff, gbase, voff) do { _Pragma("unroll") for (int _i = 0; _i < 2; ++_i) \
;         __builtin_amdgcn_global_load_lds((const unsigned*)((const char*)(gbase) + (voff)[_i]), (LAS unsigned*)(lds + (bufoff) + ldsw + _i * 8192), 16, 0, 0); } while (0)
; #define PG8_LDA(dst, b, h) do { _Pragma("unroll") for (int m = 0; m < 4; ++m) _Pragma("unroll") for (int k = 0; k < 2; ++k) dst[m][k] = *(const LAS bf16x8*)(lds + PG8_SA(b, h) + aoff + m * 2048 + k * 1024); } while (0)
; #define PG8_MMA(ai, bj, At, Bt) do { __builtin_amdgcn_s_setprio(1); _Pragma("unroll") for (int m = 0; m < 4; ++m) _Pragma("unroll") for (int n = 0; n < 2; ++n) _Pragma("unroll") for (int k = 0; k < 2; ++k) \
;         acc[ai][bj][m][n] = __builtin_amdgcn_mfma_f32_16x16x32_bf16(Bt[n][k], At[m][k], acc[ai][bj][m][n], 0, 0, 0); __builtin_amdgcn_s_setprio(0); } while (0)
; #define PG8_WAIT_V(n) asm volatile("s_waitcnt vmcnt(" #n ")" ::: "memory")
; #define PG8_WAIT_L(n) asm volatile("s_waitcnt lgkmcnt(" #n ")" ::: "memory")
; #define PG8_BAR __builtin_amdgcn_s_barrier()
; #define PG8_SCHED __builtin_amdgcn_sched_barrier(0)
; template <class Epi, class Sched>
; __device__ __forceinline__ void gemm_phase(LAS unsigned char* lds, const Gemm g, const Sched& S, const Epi& E) {
;     ...
;             PG8_LDA(At, 1, 1); PG8_STAGE(PG8_SB(1, 0), b3, voffB); PG8_STAGE(PG8_SB(1, 1), b3 + hstep, voffB); PG8_STAGE(PG8_SA(1, 0), a3, voffA);
;             PG8_WAIT_V(8); PG8_WAIT_L(0); PG8_BAR; PG8_MMA(1, 0, At, B0); PG8_MMA(1, 1, At, B1); PG8_BAR; PG8_SCHED;
;         }
	s_add_i32 s26, s49, s8
	v_lshl_add_u64 v[158:159], v[158:159], 0, s[84:85]
	s_mov_b32 m0, s26
	ds_read_b128 v[176:179], v163 offset:49152
	ds_read_b128 v[192:195], v163 offset:50176
	ds_read_b128 v[196:199], v163 offset:51200
	ds_read_b128 v[200:203], v163 offset:52224
	ds_read_b128 v[204:207], v163 offset:53248
	ds_read_b128 v[208:211], v163 offset:54272
	ds_read_b128 v[212:215], v163 offset:55296
	ds_read_b128 v[230:233], v163 offset:56320
	global_load_lds_dwordx4 v[158:159], off
	s_add_i32 m0, s26, 0x2000
	s_add_u32 s24, s24, 0x40080
	v_lshl_add_u64 v[158:159], v[216:217], 0, s[84:85]
	s_addc_u32 s25, s25, 0
	s_add_i32 s26, s50, s8
	global_load_lds_dwordx4 v[158:159], off
	v_lshl_add_u64 v[158:159], s[24:25], 0, v[184:185]
	s_mov_b32 m0, s26
	s_nop 0
	global_load_lds_dwordx4 v[158:159], off
	v_lshl_add_u64 v[158:159], s[24:25], 0, v[144:145]
	s_add_i32 m0, s26, 0x2000
	s_nop 0
	global_load_lds_dwordx4 v[158:159], off
	v_lshl_add_u64 v[158:159], v[234:235], 0, s[84:85]
	s_mov_b32 m0, s36
	s_nop 0
	global_load_lds_dwordx4 v[158:159], off
	v_lshl_add_u64 v[158:159], v[236:237], 0, s[84:85]
	s_mov_b32 m0, s37
	s_nop 0
	global_load_lds_dwordx4 v[158:159], off
	s_waitcnt vmcnt(8)
	s_waitcnt lgkmcnt(0)
	s_barrier
	s_setprio 1
	s_waitcnt lgkmcnt(0)
	v_mfma_f32_16x16x32_bf16 v[60:63], v[128:131], v[176:179], v[60:63]
	v_mfma_f32_16x16x32_bf16 v[56:59], v[136:139], v[176:179], v[56:59]
	v_mfma_f32_16x16x32_bf16 v[44:47], v[128:131], v[196:199], v[44:47]
	v_mfma_f32_16x16x32_bf16 v[40:43], v[136:139], v[196:199], v[40:43]
	v_mfma_f32_16x16x32_bf16 v[28:31], v[128:131], v[204:207], v[28:31]
	v_mfma_f32_16x16x32_bf16 v[24:27], v[136:139], v[204:207], v[24:27]
	v_mfma_f32_16x16x32_bf16 v[12:15], v[128:131], v[212:215], v[12:15]
	v_mfma_f32_16x16x32_bf16 v[8:11], v[136:139], v[212:215], v[8:11]
	v_mfma_f32_16x16x32_bf16 v[60:63], v[132:135], v[192:195], v[60:63]
	v_mfma_f32_16x16x32_bf16 v[56:59], v[140:143], v[192:195], v[56:59]
	v_mfma_f32_16x16x32_bf16 v[44:47], v[132:135], v[200:203], v[44:47]
	v_mfma_f32_16x16x32_bf16 v[40:43], v[140:143], v[200:203], v[40:43]
	v_mfma_f32_16x16x32_bf16 v[28:31], v[132:135], v[208:211], v[28:31]
	v_mfma_f32_16x16x32_bf16 v[24:27], v[140:143], v[208:211], v[24:27]
	v_mfma_f32_16x16x32_bf16 v[12:15], v[132:135], v[230:233], v[12:15]
	v_mfma_f32_16x16x32_bf16 v[8:11], v[140:143], v[230:233], v[8:11]
	s_setprio 0
	s_setprio 1
	v_mfma_f32_16x16x32_bf16 v[48:51], v[154:157], v[176:179], v[48:51]
	v_mfma_f32_16x16x32_bf16 v[52:55], v[168:171], v[176:179], v[52:55]
	v_mfma_f32_16x16x32_bf16 v[32:35], v[154:157], v[196:199], v[32:35]
	v_mfma_f32_16x16x32_bf16 v[36:39], v[168:171], v[196:199], v[36:39]
	v_mfma_f32_16x16x32_bf16 v[16:19], v[154:157], v[204:207], v[16:19]
	v_mfma_f32_16x16x32_bf16 v[20:23], v[168:171], v[204:207], v[20:23]
	v_mfma_f32_16x16x32_bf16 v[0:3], v[154:157], v[212:215], v[0:3]
	v_mfma_f32_16x16x32_bf16 v[4:7], v[168:171], v[212:215], v[4:7]
	v_mfma_f32_16x16x32_bf16 v[48:51], v[164:167], v[192:195], v[48:51]
	v_mfma_f32_16x16x32_bf16 v[52:55], v[172:175], v[192:195], v[52:55]
	v_mfma_f32_16x16x32_bf16 v[32:35], v[164:167], v[200:203], v[32:35]
	v_mfma_f32_16x16x32_bf16 v[36:39], v[172:175], v[200:203], v[36:39]
	v_mfma_f32_16x16x32_bf16 v[16:19], v[164:167], v[208:211], v[16:19]
	v_mfma_f32_16x16x32_bf16 v[20:23], v[172:175], v[208:211], v[20:23]
	v_mfma_f32_16x16x32_bf16 v[0:3], v[164:167], v[230:233], v[0:3]
	v_mfma_f32_16x16x32_bf16 v[4:7], v[172:175], v[230:233], v[4:7]
	s_setprio 0
	s_barrier
	s_add_i32 s48, s48, 2
	s_add_u32 s22, s22, 0x100
	s_addc_u32 s23, s23, 0
	s_add_u32 s46, s46, 0x100
	s_addc_u32 s47, s47, 0
	s_cmp_gt_u32 s48, 13
	s_cbranch_scc0 .LBB0_744
	s_and_b64 vcc, exec, s[6:7]
	s_cbranch_vccz .LBB0_747
	s_barrier
